# v31 + GEMM loops: removed per-segment s_setprio toggles and the redundant post-barrier lgkmcnt(0) wait (80 instrs)
# speedup vs baseline: 1.0090x; 1.0090x over previous
.LBB0_38:
	s_add_i32 s52, s20, 2
	s_add_u32 s18, s16, 0x100
	s_addc_u32 s19, s17, 0
	s_add_i32 s53, 0, 0x10000
	s_cmp_eq_u32 s9, s20
	s_cselect_b32 s23, s1, s19
	s_cselect_b32 s22, s0, s18
	s_cselect_b32 s21, s11, s51
	s_cselect_b32 s20, s10, s50
	s_add_i32 s54, 0, 0x14000
	v_add_u32_e32 v154, s53, v168
	v_add_u32_e32 v166, s54, v168
	ds_read_b128 v[142:145], v154
	ds_read_b128 v[146:149], v154 offset:1024
	ds_read_b128 v[150:153], v154 offset:2048
	ds_read_b128 v[154:157], v154 offset:3072
	ds_read_b128 v[158:161], v166
	ds_read_b128 v[162:165], v166 offset:1024
	ds_read_b128 v[172:175], v166 offset:2048
	ds_read_b128 v[176:179], v166 offset:3072
	v_lshl_add_u64 v[166:167], s[16:17], 0, v[138:139]
	s_add_i32 m0, s25, 0xc000
	ds_read_b128 v[180:183], v170
	ds_read_b128 v[184:187], v170 offset:1024
	ds_read_b128 v[188:191], v170 offset:2048
	ds_read_b128 v[192:195], v170 offset:3072
	ds_read_b128 v[196:199], v170 offset:4096
	ds_read_b128 v[200:203], v170 offset:5120
	ds_read_b128 v[204:207], v170 offset:6144
	ds_read_b128 v[208:211], v170 offset:7168
	global_load_lds_dwordx4 v[166:167], off
	v_lshl_add_u64 v[166:167], s[16:17], 0, v[140:141]
	s_add_i32 m0, s25, 0xe000
	s_nop 0
	global_load_lds_dwordx4 v[166:167], off
	s_waitcnt vmcnt(8)
	s_waitcnt lgkmcnt(0)
	s_barrier
	v_mfma_f32_16x16x32_bf16 v[130:133], v[142:145], v[180:183], v[130:133]
	v_mfma_f32_16x16x32_bf16 v[126:129], v[150:153], v[180:183], v[126:129]
	v_mfma_f32_16x16x32_bf16 v[122:125], v[142:145], v[188:191], v[122:125]
	v_mfma_f32_16x16x32_bf16 v[118:121], v[150:153], v[188:191], v[118:121]
	v_mfma_f32_16x16x32_bf16 v[114:117], v[142:145], v[196:199], v[114:117]
	v_mfma_f32_16x16x32_bf16 v[110:113], v[150:153], v[196:199], v[110:113]
	v_mfma_f32_16x16x32_bf16 v[106:109], v[142:145], v[204:207], v[106:109]
	v_mfma_f32_16x16x32_bf16 v[102:105], v[150:153], v[204:207], v[102:105]
	v_mfma_f32_16x16x32_bf16 v[130:133], v[146:149], v[184:187], v[130:133]
	v_mfma_f32_16x16x32_bf16 v[126:129], v[154:157], v[184:187], v[126:129]
	v_mfma_f32_16x16x32_bf16 v[122:125], v[146:149], v[192:195], v[122:125]
	v_mfma_f32_16x16x32_bf16 v[118:121], v[154:157], v[192:195], v[118:121]
	v_mfma_f32_16x16x32_bf16 v[114:117], v[146:149], v[200:203], v[114:117]
	v_mfma_f32_16x16x32_bf16 v[110:113], v[154:157], v[200:203], v[110:113]
	v_mfma_f32_16x16x32_bf16 v[106:109], v[146:149], v[208:211], v[106:109]
	v_mfma_f32_16x16x32_bf16 v[102:105], v[154:157], v[208:211], v[102:105]
	v_mfma_f32_16x16x32_bf16 v[98:101], v[158:161], v[180:183], v[98:101]
	v_mfma_f32_16x16x32_bf16 v[94:97], v[172:175], v[180:183], v[94:97]
	v_mfma_f32_16x16x32_bf16 v[90:93], v[158:161], v[188:191], v[90:93]
	v_mfma_f32_16x16x32_bf16 v[86:89], v[172:175], v[188:191], v[86:89]
	v_mfma_f32_16x16x32_bf16 v[82:85], v[158:161], v[196:199], v[82:85]
	v_mfma_f32_16x16x32_bf16 v[78:81], v[172:175], v[196:199], v[78:81]
	v_mfma_f32_16x16x32_bf16 v[74:77], v[158:161], v[204:207], v[74:77]
	v_mfma_f32_16x16x32_bf16 v[70:73], v[172:175], v[204:207], v[70:73]
	v_mfma_f32_16x16x32_bf16 v[98:101], v[162:165], v[184:187], v[98:101]
	v_mfma_f32_16x16x32_bf16 v[94:97], v[176:179], v[184:187], v[94:97]
	v_mfma_f32_16x16x32_bf16 v[90:93], v[162:165], v[192:195], v[90:93]
	v_mfma_f32_16x16x32_bf16 v[86:89], v[176:179], v[192:195], v[86:89]
	v_mfma_f32_16x16x32_bf16 v[82:85], v[162:165], v[200:203], v[82:85]
	v_mfma_f32_16x16x32_bf16 v[78:81], v[176:179], v[200:203], v[78:81]
	v_mfma_f32_16x16x32_bf16 v[74:77], v[162:165], v[208:211], v[74:77]
	v_mfma_f32_16x16x32_bf16 v[70:73], v[176:179], v[208:211], v[70:73]
	s_barrier
	s_add_i32 s16, s53, s24
	v_lshl_add_u64 v[166:167], s[20:21], 0, v[0:1]
	s_mov_b32 m0, s16
	ds_read_b128 v[180:183], v170 offset:16384
	ds_read_b128 v[184:187], v170 offset:17408
	ds_read_b128 v[188:191], v170 offset:18432
	ds_read_b128 v[192:195], v170 offset:19456
	ds_read_b128 v[196:199], v170 offset:20480
	ds_read_b128 v[200:203], v170 offset:21504
	ds_read_b128 v[204:207], v170 offset:22528
	ds_read_b128 v[208:211], v170 offset:23552
	global_load_lds_dwordx4 v[166:167], off
	s_add_i32 m0, s16, 0x2000
	s_add_u32 s16, s20, 0xc0000
	v_lshl_add_u64 v[212:213], s[20:21], 0, v[136:137]
	s_addc_u32 s17, s21, 0
	s_add_i32 s53, s54, s24
	global_load_lds_dwordx4 v[212:213], off
	v_lshl_add_u64 v[214:215], s[16:17], 0, v[0:1]
	s_mov_b32 m0, s53
	v_lshl_add_u64 v[216:217], s[22:23], 0, v[134:135]
	global_load_lds_dwordx4 v[214:215], off
	v_lshl_add_u64 v[214:215], s[16:17], 0, v[136:137]
	s_add_i32 m0, s53, 0x2000
	s_nop 0
	global_load_lds_dwordx4 v[214:215], off
	v_lshl_add_u64 v[214:215], s[22:23], 0, v[14:15]
	s_mov_b32 m0, s25
	s_nop 0
	global_load_lds_dwordx4 v[214:215], off
	s_mov_b32 m0, s26
	s_nop 0
	global_load_lds_dwordx4 v[216:217], off
	s_waitcnt vmcnt(8)
	s_waitcnt lgkmcnt(0)
	s_barrier
	v_mfma_f32_16x16x32_bf16 v[66:69], v[142:145], v[180:183], v[66:69]
	v_mfma_f32_16x16x32_bf16 v[62:65], v[150:153], v[180:183], v[62:65]
	v_mfma_f32_16x16x32_bf16 v[58:61], v[142:145], v[188:191], v[58:61]
	v_mfma_f32_16x16x32_bf16 v[54:57], v[150:153], v[188:191], v[54:57]
	v_mfma_f32_16x16x32_bf16 v[50:53], v[142:145], v[196:199], v[50:53]
	v_mfma_f32_16x16x32_bf16 v[46:49], v[150:153], v[196:199], v[46:49]
	v_mfma_f32_16x16x32_bf16 v[42:45], v[142:145], v[204:207], v[42:45]
	v_mfma_f32_16x16x32_bf16 v[38:41], v[150:153], v[204:207], v[38:41]
	v_mfma_f32_16x16x32_bf16 v[66:69], v[146:149], v[184:187], v[66:69]
	v_mfma_f32_16x16x32_bf16 v[62:65], v[154:157], v[184:187], v[62:65]
	v_mfma_f32_16x16x32_bf16 v[58:61], v[146:149], v[192:195], v[58:61]
	v_mfma_f32_16x16x32_bf16 v[54:57], v[154:157], v[192:195], v[54:57]
	v_mfma_f32_16x16x32_bf16 v[50:53], v[146:149], v[200:203], v[50:53]
	v_mfma_f32_16x16x32_bf16 v[46:49], v[154:157], v[200:203], v[46:49]
	v_mfma_f32_16x16x32_bf16 v[42:45], v[146:149], v[208:211], v[42:45]
	v_mfma_f32_16x16x32_bf16 v[38:41], v[154:157], v[208:211], v[38:41]
	v_mfma_f32_16x16x32_bf16 v[34:37], v[158:161], v[180:183], v[34:37]
	v_mfma_f32_16x16x32_bf16 v[30:33], v[172:175], v[180:183], v[30:33]
	v_mfma_f32_16x16x32_bf16 v[26:29], v[158:161], v[188:191], v[26:29]
	v_mfma_f32_16x16x32_bf16 v[22:25], v[172:175], v[188:191], v[22:25]
	v_mfma_f32_16x16x32_bf16 v[18:21], v[158:161], v[196:199], v[18:21]
	v_mfma_f32_16x16x32_bf16 v[10:13], v[172:175], v[196:199], v[10:13]
	v_mfma_f32_16x16x32_bf16 v[6:9], v[158:161], v[204:207], v[6:9]
	v_mfma_f32_16x16x32_bf16 v[2:5], v[172:175], v[204:207], v[2:5]
	v_mfma_f32_16x16x32_bf16 v[34:37], v[162:165], v[184:187], v[34:37]
	v_mfma_f32_16x16x32_bf16 v[30:33], v[176:179], v[184:187], v[30:33]
	v_mfma_f32_16x16x32_bf16 v[26:29], v[162:165], v[192:195], v[26:29]
	v_mfma_f32_16x16x32_bf16 v[22:25], v[176:179], v[192:195], v[22:25]
	v_mfma_f32_16x16x32_bf16 v[18:21], v[162:165], v[200:203], v[18:21]
	v_mfma_f32_16x16x32_bf16 v[10:13], v[176:179], v[200:203], v[10:13]
	v_mfma_f32_16x16x32_bf16 v[6:9], v[162:165], v[208:211], v[6:9]
	v_mfma_f32_16x16x32_bf16 v[2:5], v[176:179], v[208:211], v[2:5]
	s_barrier
	s_add_i32 s53, 0, 0x18000
	s_add_i32 s54, 0, 0x1c000
	v_add_u32_e32 v154, s53, v168
	v_add_u32_e32 v171, s54, v168
	ds_read_b128 v[142:145], v154
	ds_read_b128 v[146:149], v154 offset:1024
	ds_read_b128 v[150:153], v154 offset:2048
	ds_read_b128 v[154:157], v154 offset:3072
	ds_read_b128 v[158:161], v171
	ds_read_b128 v[162:165], v171 offset:1024
	ds_read_b128 v[172:175], v171 offset:2048
	ds_read_b128 v[176:179], v171 offset:3072
	s_add_u32 s16, s22, 0xc0000
	s_addc_u32 s17, s23, 0
	s_mov_b32 m0, s27
	v_lshl_add_u64 v[218:219], s[16:17], 0, v[14:15]
	ds_read_b128 v[180:183], v170 offset:32768
	ds_read_b128 v[184:187], v170 offset:33792
	ds_read_b128 v[188:191], v170 offset:34816
	ds_read_b128 v[192:195], v170 offset:35840
	ds_read_b128 v[196:199], v170 offset:36864
	ds_read_b128 v[200:203], v170 offset:37888
	ds_read_b128 v[204:207], v170 offset:38912
	ds_read_b128 v[208:211], v170 offset:39936
	global_load_lds_dwordx4 v[218:219], off
	v_lshl_add_u64 v[218:219], s[16:17], 0, v[134:135]
	s_mov_b32 m0, s33
	s_nop 0
	global_load_lds_dwordx4 v[218:219], off
	s_waitcnt vmcnt(8)
	s_waitcnt lgkmcnt(0)
	s_barrier
	v_mfma_f32_16x16x32_bf16 v[130:133], v[142:145], v[180:183], v[130:133]
	v_mfma_f32_16x16x32_bf16 v[126:129], v[150:153], v[180:183], v[126:129]
	v_mfma_f32_16x16x32_bf16 v[122:125], v[142:145], v[188:191], v[122:125]
	v_mfma_f32_16x16x32_bf16 v[118:121], v[150:153], v[188:191], v[118:121]
	v_mfma_f32_16x16x32_bf16 v[114:117], v[142:145], v[196:199], v[114:117]
	v_mfma_f32_16x16x32_bf16 v[110:113], v[150:153], v[196:199], v[110:113]
	v_mfma_f32_16x16x32_bf16 v[106:109], v[142:145], v[204:207], v[106:109]
	v_mfma_f32_16x16x32_bf16 v[102:105], v[150:153], v[204:207], v[102:105]
	v_mfma_f32_16x16x32_bf16 v[130:133], v[146:149], v[184:187], v[130:133]
	v_mfma_f32_16x16x32_bf16 v[126:129], v[154:157], v[184:187], v[126:129]
	v_mfma_f32_16x16x32_bf16 v[122:125], v[146:149], v[192:195], v[122:125]
	v_mfma_f32_16x16x32_bf16 v[118:121], v[154:157], v[192:195], v[118:121]
	v_mfma_f32_16x16x32_bf16 v[114:117], v[146:149], v[200:203], v[114:117]
	v_mfma_f32_16x16x32_bf16 v[110:113], v[154:157], v[200:203], v[110:113]
	v_mfma_f32_16x16x32_bf16 v[106:109], v[146:149], v[208:211], v[106:109]
	v_mfma_f32_16x16x32_bf16 v[102:105], v[154:157], v[208:211], v[102:105]
	v_mfma_f32_16x16x32_bf16 v[98:101], v[158:161], v[180:183], v[98:101]
	v_mfma_f32_16x16x32_bf16 v[94:97], v[172:175], v[180:183], v[94:97]
	v_mfma_f32_16x16x32_bf16 v[90:93], v[158:161], v[188:191], v[90:93]
	v_mfma_f32_16x16x32_bf16 v[86:89], v[172:175], v[188:191], v[86:89]
	v_mfma_f32_16x16x32_bf16 v[82:85], v[158:161], v[196:199], v[82:85]
	v_mfma_f32_16x16x32_bf16 v[78:81], v[172:175], v[196:199], v[78:81]
	v_mfma_f32_16x16x32_bf16 v[74:77], v[158:161], v[204:207], v[74:77]
	v_mfma_f32_16x16x32_bf16 v[70:73], v[172:175], v[204:207], v[70:73]
	v_mfma_f32_16x16x32_bf16 v[98:101], v[162:165], v[184:187], v[98:101]
	v_mfma_f32_16x16x32_bf16 v[94:97], v[176:179], v[184:187], v[94:97]
	v_mfma_f32_16x16x32_bf16 v[90:93], v[162:165], v[192:195], v[90:93]
	v_mfma_f32_16x16x32_bf16 v[86:89], v[176:179], v[192:195], v[86:89]
	v_mfma_f32_16x16x32_bf16 v[82:85], v[162:165], v[200:203], v[82:85]
	v_mfma_f32_16x16x32_bf16 v[78:81], v[176:179], v[200:203], v[78:81]
	v_mfma_f32_16x16x32_bf16 v[74:77], v[162:165], v[208:211], v[74:77]
	v_mfma_f32_16x16x32_bf16 v[70:73], v[176:179], v[208:211], v[70:73]
	s_barrier
	s_add_i32 s16, s53, s24
	v_lshl_add_u64 v[166:167], v[166:167], 0, s[36:37]
	s_mov_b32 m0, s16
	ds_read_b128 v[180:183], v170 offset:49152
	ds_read_b128 v[184:187], v170 offset:50176
	ds_read_b128 v[188:191], v170 offset:51200
	ds_read_b128 v[192:195], v170 offset:52224
	ds_read_b128 v[196:199], v170 offset:53248
	ds_read_b128 v[200:203], v170 offset:54272
	ds_read_b128 v[204:207], v170 offset:55296
	ds_read_b128 v[208:211], v170 offset:56320
	global_load_lds_dwordx4 v[166:167], off
	s_add_i32 m0, s16, 0x2000
	s_add_u32 s16, s20, 0xc0080
	v_lshl_add_u64 v[166:167], v[212:213], 0, s[36:37]
	s_addc_u32 s17, s21, 0
	s_add_i32 s20, s54, s24
	global_load_lds_dwordx4 v[166:167], off
	v_lshl_add_u64 v[166:167], s[16:17], 0, v[0:1]
	s_mov_b32 m0, s20
	s_nop 0
	global_load_lds_dwordx4 v[166:167], off
	v_lshl_add_u64 v[166:167], s[16:17], 0, v[136:137]
	s_add_i32 m0, s20, 0x2000
	s_nop 0
	global_load_lds_dwordx4 v[166:167], off
	v_lshl_add_u64 v[166:167], v[214:215], 0, s[36:37]
	s_mov_b32 m0, s45
	s_nop 0
	global_load_lds_dwordx4 v[166:167], off
	v_lshl_add_u64 v[166:167], v[216:217], 0, s[36:37]
	s_mov_b32 m0, s46
	s_nop 0
	global_load_lds_dwordx4 v[166:167], off
	s_waitcnt vmcnt(8)
	s_waitcnt lgkmcnt(0)
	s_barrier
	v_mfma_f32_16x16x32_bf16 v[66:69], v[142:145], v[180:183], v[66:69]
	v_mfma_f32_16x16x32_bf16 v[62:65], v[150:153], v[180:183], v[62:65]
	v_mfma_f32_16x16x32_bf16 v[58:61], v[142:145], v[188:191], v[58:61]
	v_mfma_f32_16x16x32_bf16 v[54:57], v[150:153], v[188:191], v[54:57]
	v_mfma_f32_16x16x32_bf16 v[50:53], v[142:145], v[196:199], v[50:53]
	v_mfma_f32_16x16x32_bf16 v[46:49], v[150:153], v[196:199], v[46:49]
	v_mfma_f32_16x16x32_bf16 v[42:45], v[142:145], v[204:207], v[42:45]
	v_mfma_f32_16x16x32_bf16 v[38:41], v[150:153], v[204:207], v[38:41]
	v_mfma_f32_16x16x32_bf16 v[66:69], v[146:149], v[184:187], v[66:69]
	v_mfma_f32_16x16x32_bf16 v[62:65], v[154:157], v[184:187], v[62:65]
	v_mfma_f32_16x16x32_bf16 v[58:61], v[146:149], v[192:195], v[58:61]
	v_mfma_f32_16x16x32_bf16 v[54:57], v[154:157], v[192:195], v[54:57]
	v_mfma_f32_16x16x32_bf16 v[50:53], v[146:149], v[200:203], v[50:53]
	v_mfma_f32_16x16x32_bf16 v[46:49], v[154:157], v[200:203], v[46:49]
	v_mfma_f32_16x16x32_bf16 v[42:45], v[146:149], v[208:211], v[42:45]
	v_mfma_f32_16x16x32_bf16 v[38:41], v[154:157], v[208:211], v[38:41]
	v_mfma_f32_16x16x32_bf16 v[34:37], v[158:161], v[180:183], v[34:37]
	v_mfma_f32_16x16x32_bf16 v[30:33], v[172:175], v[180:183], v[30:33]
	v_mfma_f32_16x16x32_bf16 v[26:29], v[158:161], v[188:191], v[26:29]
	v_mfma_f32_16x16x32_bf16 v[22:25], v[172:175], v[188:191], v[22:25]
	v_mfma_f32_16x16x32_bf16 v[18:21], v[158:161], v[196:199], v[18:21]
	v_mfma_f32_16x16x32_bf16 v[10:13], v[172:175], v[196:199], v[10:13]
	v_mfma_f32_16x16x32_bf16 v[6:9], v[158:161], v[204:207], v[6:9]
	v_mfma_f32_16x16x32_bf16 v[2:5], v[172:175], v[204:207], v[2:5]
	v_mfma_f32_16x16x32_bf16 v[34:37], v[162:165], v[184:187], v[34:37]
	v_mfma_f32_16x16x32_bf16 v[30:33], v[176:179], v[184:187], v[30:33]
	v_mfma_f32_16x16x32_bf16 v[26:29], v[162:165], v[192:195], v[26:29]
	v_mfma_f32_16x16x32_bf16 v[22:25], v[176:179], v[192:195], v[22:25]
	v_mfma_f32_16x16x32_bf16 v[18:21], v[162:165], v[200:203], v[18:21]
	v_mfma_f32_16x16x32_bf16 v[10:13], v[176:179], v[200:203], v[10:13]
	v_mfma_f32_16x16x32_bf16 v[6:9], v[162:165], v[208:211], v[6:9]
	v_mfma_f32_16x16x32_bf16 v[2:5], v[176:179], v[208:211], v[2:5]
	s_barrier
	s_add_u32 s50, s50, 0x100
	s_addc_u32 s51, s51, 0
	s_cmp_ge_i32 s52, s43
	s_mov_b64 s[16:17], s[18:19]
	s_mov_b32 s20, s52
	s_cbranch_scc0 .LBB0_38
	s_and_b64 vcc, exec, s[6:7]
	s_cbranch_vccz .LBB0_41
	s_barrier

.LBB0_164:
	s_add_u32 s24, s18, 0xfff80080
	s_addc_u32 s25, s19, -1
	s_add_i32 s52, 0, 0x10000
	s_cmp_eq_u32 s51, 28
	s_cselect_b32 s47, s9, s25
	s_cselect_b32 s46, s21, s24
	v_add_u32_e32 v6, s52, v172
	s_cselect_b32 s25, s1, s50
	s_cselect_b32 s24, s23, s29
	s_add_i32 s54, 0, 0x14000
	ds_read_b128 v[126:129], v6
	ds_read_b128 v[130:133], v6 offset:1024
	ds_read_b128 v[142:145], v6 offset:2048
	ds_read_b128 v[146:149], v6 offset:3072
	v_add_u32_e32 v6, s54, v172
	ds_read_b128 v[166:169], v6
	ds_read_b128 v[204:207], v6 offset:1024
	ds_read_b128 v[208:211], v6 offset:2048
	ds_read_b128 v[216:219], v6 offset:3072
	v_lshl_add_u64 v[6:7], s[18:19], 0, v[162:163]
	s_add_i32 m0, s79, 0xc000
	ds_read_b128 v[220:223], v198
	ds_read_b128 v[224:227], v198 offset:1024
	ds_read_b128 v[228:231], v198 offset:2048
	ds_read_b128 v[232:235], v198 offset:3072
	ds_read_b128 v[236:239], v198 offset:4096
	ds_read_b128 v[240:243], v198 offset:5120
	ds_read_b128 v[244:247], v198 offset:6144
	ds_read_b128 v[248:251], v198 offset:7168
	global_load_lds_dwordx4 v[6:7], off
	v_lshl_add_u64 v[6:7], s[18:19], 0, v[164:165]
	s_add_i32 m0, s79, 0xe000
	s_nop 0
	global_load_lds_dwordx4 v[6:7], off
	s_waitcnt vmcnt(8)
	s_waitcnt lgkmcnt(0)
	s_barrier
	v_mfma_f32_16x16x32_bf16 v[138:141], v[126:129], v[220:223], v[138:141]
	v_mfma_f32_16x16x32_bf16 v[134:137], v[142:145], v[220:223], v[134:137]
	v_mfma_f32_16x16x32_bf16 v[122:125], v[126:129], v[228:231], v[122:125]
	v_mfma_f32_16x16x32_bf16 v[118:121], v[142:145], v[228:231], v[118:121]
	v_mfma_f32_16x16x32_bf16 v[106:109], v[126:129], v[236:239], v[106:109]
	v_mfma_f32_16x16x32_bf16 v[102:105], v[142:145], v[236:239], v[102:105]
	v_mfma_f32_16x16x32_bf16 v[90:93], v[126:129], v[244:247], v[90:93]
	v_mfma_f32_16x16x32_bf16 v[86:89], v[142:145], v[244:247], v[86:89]
	v_mfma_f32_16x16x32_bf16 v[138:141], v[130:133], v[224:227], v[138:141]
	v_mfma_f32_16x16x32_bf16 v[134:137], v[146:149], v[224:227], v[134:137]
	v_mfma_f32_16x16x32_bf16 v[122:125], v[130:133], v[232:235], v[122:125]
	v_mfma_f32_16x16x32_bf16 v[118:121], v[146:149], v[232:235], v[118:121]
	v_mfma_f32_16x16x32_bf16 v[106:109], v[130:133], v[240:243], v[106:109]
	v_mfma_f32_16x16x32_bf16 v[102:105], v[146:149], v[240:243], v[102:105]
	v_mfma_f32_16x16x32_bf16 v[90:93], v[130:133], v[248:251], v[90:93]
	v_mfma_f32_16x16x32_bf16 v[86:89], v[146:149], v[248:251], v[86:89]
	v_mfma_f32_16x16x32_bf16 v[114:117], v[166:169], v[220:223], v[114:117]
	v_mfma_f32_16x16x32_bf16 v[110:113], v[208:211], v[220:223], v[110:113]
	v_mfma_f32_16x16x32_bf16 v[98:101], v[166:169], v[228:231], v[98:101]
	v_mfma_f32_16x16x32_bf16 v[94:97], v[208:211], v[228:231], v[94:97]
	v_mfma_f32_16x16x32_bf16 v[82:85], v[166:169], v[236:239], v[82:85]
	v_mfma_f32_16x16x32_bf16 v[78:81], v[208:211], v[236:239], v[78:81]
	v_mfma_f32_16x16x32_bf16 v[66:69], v[166:169], v[244:247], v[66:69]
	v_mfma_f32_16x16x32_bf16 v[62:65], v[208:211], v[244:247], v[62:65]
	v_mfma_f32_16x16x32_bf16 v[114:117], v[204:207], v[224:227], v[114:117]
	v_mfma_f32_16x16x32_bf16 v[110:113], v[216:219], v[224:227], v[110:113]
	v_mfma_f32_16x16x32_bf16 v[98:101], v[204:207], v[232:235], v[98:101]
	v_mfma_f32_16x16x32_bf16 v[94:97], v[216:219], v[232:235], v[94:97]
	v_mfma_f32_16x16x32_bf16 v[82:85], v[204:207], v[240:243], v[82:85]
	v_mfma_f32_16x16x32_bf16 v[78:81], v[216:219], v[240:243], v[78:81]
	v_mfma_f32_16x16x32_bf16 v[66:69], v[204:207], v[248:251], v[66:69]
	v_mfma_f32_16x16x32_bf16 v[62:65], v[216:219], v[248:251], v[62:65]
	s_barrier
	s_add_i32 s52, s52, s33
	v_lshl_add_u64 v[170:171], s[24:25], 0, v[0:1]
	s_mov_b32 m0, s52
	ds_read_b128 v[220:223], v198 offset:16384
	ds_read_b128 v[224:227], v198 offset:17408
	ds_read_b128 v[228:231], v198 offset:18432
	ds_read_b128 v[232:235], v198 offset:19456
	ds_read_b128 v[236:239], v198 offset:20480
	ds_read_b128 v[240:243], v198 offset:21504
	ds_read_b128 v[244:247], v198 offset:22528
	ds_read_b128 v[248:251], v198 offset:23552
	global_load_lds_dwordx4 v[170:171], off
	s_add_i32 m0, s52, 0x2000
	s_add_u32 s52, s24, 0x80000
	v_lshl_add_u64 v[200:201], s[24:25], 0, v[154:155]
	s_addc_u32 s53, s25, 0
	s_add_i32 s54, s54, s33
	global_load_lds_dwordx4 v[200:201], off
	v_lshl_add_u64 v[6:7], s[52:53], 0, v[0:1]
	s_mov_b32 m0, s54
	v_lshl_add_u64 v[202:203], s[46:47], 0, v[150:151]
	global_load_lds_dwordx4 v[6:7], off
	v_lshl_add_u64 v[6:7], s[52:53], 0, v[154:155]
	s_add_i32 m0, s54, 0x2000
	v_lshl_add_u64 v[212:213], s[46:47], 0, v[152:153]
	global_load_lds_dwordx4 v[6:7], off
	s_mov_b32 m0, s79
	s_nop 0
	global_load_lds_dwordx4 v[202:203], off
	s_mov_b32 m0, s81
	s_nop 0
	global_load_lds_dwordx4 v[212:213], off
	s_waitcnt vmcnt(8)
	s_waitcnt lgkmcnt(0)
	s_barrier
	v_mfma_f32_16x16x32_bf16 v[74:77], v[126:129], v[220:223], v[74:77]
	v_mfma_f32_16x16x32_bf16 v[70:73], v[142:145], v[220:223], v[70:73]
	v_mfma_f32_16x16x32_bf16 v[58:61], v[126:129], v[228:231], v[58:61]
	v_mfma_f32_16x16x32_bf16 v[54:57], v[142:145], v[228:231], v[54:57]
	v_mfma_f32_16x16x32_bf16 v[42:45], v[126:129], v[236:239], v[42:45]
	v_mfma_f32_16x16x32_bf16 v[38:41], v[142:145], v[236:239], v[38:41]
	v_mfma_f32_16x16x32_bf16 v[22:25], v[126:129], v[244:247], v[22:25]
	v_mfma_f32_16x16x32_bf16 v[18:21], v[142:145], v[244:247], v[18:21]
	v_mfma_f32_16x16x32_bf16 v[74:77], v[130:133], v[224:227], v[74:77]
	v_mfma_f32_16x16x32_bf16 v[70:73], v[146:149], v[224:227], v[70:73]
	v_mfma_f32_16x16x32_bf16 v[58:61], v[130:133], v[232:235], v[58:61]
	v_mfma_f32_16x16x32_bf16 v[54:57], v[146:149], v[232:235], v[54:57]
	v_mfma_f32_16x16x32_bf16 v[42:45], v[130:133], v[240:243], v[42:45]
	v_mfma_f32_16x16x32_bf16 v[38:41], v[146:149], v[240:243], v[38:41]
	v_mfma_f32_16x16x32_bf16 v[22:25], v[130:133], v[248:251], v[22:25]
	v_mfma_f32_16x16x32_bf16 v[18:21], v[146:149], v[248:251], v[18:21]
	v_mfma_f32_16x16x32_bf16 v[50:53], v[166:169], v[220:223], v[50:53]
	v_mfma_f32_16x16x32_bf16 v[46:49], v[208:211], v[220:223], v[46:49]
	v_mfma_f32_16x16x32_bf16 v[34:37], v[166:169], v[228:231], v[34:37]
	v_mfma_f32_16x16x32_bf16 v[30:33], v[208:211], v[228:231], v[30:33]
	v_mfma_f32_16x16x32_bf16 v[26:29], v[166:169], v[236:239], v[26:29]
	v_mfma_f32_16x16x32_bf16 v[2:5], v[208:211], v[236:239], v[2:5]
	v_mfma_f32_16x16x32_bf16 v[12:15], v[166:169], v[244:247], v[12:15]
	v_mfma_f32_16x16x32_bf16 v[6:9], v[208:211], v[244:247], v[8:11]
	v_mfma_f32_16x16x32_bf16 v[50:53], v[204:207], v[224:227], v[50:53]
	v_mfma_f32_16x16x32_bf16 v[46:49], v[216:219], v[224:227], v[46:49]
	v_mfma_f32_16x16x32_bf16 v[34:37], v[204:207], v[232:235], v[34:37]
	v_mfma_f32_16x16x32_bf16 v[30:33], v[216:219], v[232:235], v[30:33]
	v_mfma_f32_16x16x32_bf16 v[26:29], v[204:207], v[240:243], v[26:29]
	v_mfma_f32_16x16x32_bf16 v[2:5], v[216:219], v[240:243], v[2:5]
	v_mfma_f32_16x16x32_bf16 v[12:15], v[204:207], v[248:251], v[12:15]
	v_mfma_f32_16x16x32_bf16 v[6:9], v[216:219], v[248:251], v[6:9]
	s_barrier
	s_add_i32 s52, 0, 0x18000
	v_add_u32_e32 v10, s52, v172
	s_add_i32 s53, 0, 0x1c000
	ds_read_b128 v[126:129], v10
	ds_read_b128 v[130:133], v10 offset:1024
	ds_read_b128 v[142:145], v10 offset:2048
	ds_read_b128 v[146:149], v10 offset:3072
	v_add_u32_e32 v10, s53, v172
	ds_read_b128 v[166:169], v10
	ds_read_b128 v[204:207], v10 offset:1024
	ds_read_b128 v[208:211], v10 offset:2048
	ds_read_b128 v[216:219], v10 offset:3072
	s_add_u32 s46, s46, 0x80000
	s_addc_u32 s47, s47, 0
	s_mov_b32 m0, s82
	v_lshl_add_u64 v[10:11], s[46:47], 0, v[150:151]
	ds_read_b128 v[220:223], v198 offset:32768
	ds_read_b128 v[224:227], v198 offset:33792
	ds_read_b128 v[228:231], v198 offset:34816
	ds_read_b128 v[232:235], v198 offset:35840
	ds_read_b128 v[236:239], v198 offset:36864
	ds_read_b128 v[240:243], v198 offset:37888
	ds_read_b128 v[244:247], v198 offset:38912
	ds_read_b128 v[248:251], v198 offset:39936
	global_load_lds_dwordx4 v[10:11], off
	v_lshl_add_u64 v[10:11], s[46:47], 0, v[152:153]
	s_mov_b32 m0, s83
	s_nop 0
	global_load_lds_dwordx4 v[10:11], off
	s_waitcnt vmcnt(8)
	s_waitcnt lgkmcnt(0)
	s_barrier
	v_mfma_f32_16x16x32_bf16 v[138:141], v[126:129], v[220:223], v[138:141]
	v_mfma_f32_16x16x32_bf16 v[134:137], v[142:145], v[220:223], v[134:137]
	v_mfma_f32_16x16x32_bf16 v[122:125], v[126:129], v[228:231], v[122:125]
	v_mfma_f32_16x16x32_bf16 v[118:121], v[142:145], v[228:231], v[118:121]
	v_mfma_f32_16x16x32_bf16 v[106:109], v[126:129], v[236:239], v[106:109]
	v_mfma_f32_16x16x32_bf16 v[102:105], v[142:145], v[236:239], v[102:105]
	v_mfma_f32_16x16x32_bf16 v[90:93], v[126:129], v[244:247], v[90:93]
	v_mfma_f32_16x16x32_bf16 v[86:89], v[142:145], v[244:247], v[86:89]
	v_mfma_f32_16x16x32_bf16 v[138:141], v[130:133], v[224:227], v[138:141]
	v_mfma_f32_16x16x32_bf16 v[134:137], v[146:149], v[224:227], v[134:137]
	v_mfma_f32_16x16x32_bf16 v[122:125], v[130:133], v[232:235], v[122:125]
	v_mfma_f32_16x16x32_bf16 v[118:121], v[146:149], v[232:235], v[118:121]
	v_mfma_f32_16x16x32_bf16 v[106:109], v[130:133], v[240:243], v[106:109]
	v_mfma_f32_16x16x32_bf16 v[102:105], v[146:149], v[240:243], v[102:105]
	v_mfma_f32_16x16x32_bf16 v[90:93], v[130:133], v[248:251], v[90:93]
	v_mfma_f32_16x16x32_bf16 v[86:89], v[146:149], v[248:251], v[86:89]
	v_mfma_f32_16x16x32_bf16 v[114:117], v[166:169], v[220:223], v[114:117]
	v_mfma_f32_16x16x32_bf16 v[110:113], v[208:211], v[220:223], v[110:113]
	v_mfma_f32_16x16x32_bf16 v[98:101], v[166:169], v[228:231], v[98:101]
	v_mfma_f32_16x16x32_bf16 v[94:97], v[208:211], v[228:231], v[94:97]
	v_mfma_f32_16x16x32_bf16 v[82:85], v[166:169], v[236:239], v[82:85]
	v_mfma_f32_16x16x32_bf16 v[78:81], v[208:211], v[236:239], v[78:81]
	v_mfma_f32_16x16x32_bf16 v[66:69], v[166:169], v[244:247], v[66:69]
	v_mfma_f32_16x16x32_bf16 v[62:65], v[208:211], v[244:247], v[62:65]
	v_mfma_f32_16x16x32_bf16 v[114:117], v[204:207], v[224:227], v[114:117]
	v_mfma_f32_16x16x32_bf16 v[110:113], v[216:219], v[224:227], v[110:113]
	v_mfma_f32_16x16x32_bf16 v[98:101], v[204:207], v[232:235], v[98:101]
	v_mfma_f32_16x16x32_bf16 v[94:97], v[216:219], v[232:235], v[94:97]
	v_mfma_f32_16x16x32_bf16 v[82:85], v[204:207], v[240:243], v[82:85]
	v_mfma_f32_16x16x32_bf16 v[78:81], v[216:219], v[240:243], v[78:81]
	v_mfma_f32_16x16x32_bf16 v[66:69], v[204:207], v[248:251], v[66:69]
	v_mfma_f32_16x16x32_bf16 v[62:65], v[216:219], v[248:251], v[62:65]
	s_barrier
	s_add_i32 s46, s52, s33
	v_lshl_add_u64 v[10:11], v[170:171], 0, s[36:37]
	s_mov_b32 m0, s46
	ds_read_b128 v[220:223], v198 offset:49152
	ds_read_b128 v[224:227], v198 offset:50176
	ds_read_b128 v[228:231], v198 offset:51200
	ds_read_b128 v[232:235], v198 offset:52224
	ds_read_b128 v[236:239], v198 offset:53248
	ds_read_b128 v[240:243], v198 offset:54272
	ds_read_b128 v[244:247], v198 offset:55296
	ds_read_b128 v[248:251], v198 offset:56320
	global_load_lds_dwordx4 v[10:11], off
	s_add_i32 m0, s46, 0x2000
	s_add_u32 s24, s24, 0x80080
	v_lshl_add_u64 v[10:11], v[200:201], 0, s[36:37]
	s_addc_u32 s25, s25, 0
	s_add_i32 s46, s53, s33
	global_load_lds_dwordx4 v[10:11], off
	v_lshl_add_u64 v[10:11], s[24:25], 0, v[0:1]
	s_mov_b32 m0, s46
	s_nop 0
	global_load_lds_dwordx4 v[10:11], off
	v_lshl_add_u64 v[10:11], s[24:25], 0, v[154:155]
	s_add_i32 m0, s46, 0x2000
	s_nop 0
	global_load_lds_dwordx4 v[10:11], off
	v_lshl_add_u64 v[10:11], v[202:203], 0, s[36:37]
	s_mov_b32 m0, s94
	s_nop 0
	global_load_lds_dwordx4 v[10:11], off
	v_lshl_add_u64 v[10:11], v[212:213], 0, s[36:37]
	s_mov_b32 m0, s95
	s_nop 0
	global_load_lds_dwordx4 v[10:11], off
	s_waitcnt vmcnt(8)
	s_waitcnt lgkmcnt(0)
	s_barrier
	v_mfma_f32_16x16x32_bf16 v[74:77], v[126:129], v[220:223], v[74:77]
	v_mfma_f32_16x16x32_bf16 v[70:73], v[142:145], v[220:223], v[70:73]
	v_mfma_f32_16x16x32_bf16 v[58:61], v[126:129], v[228:231], v[58:61]
	v_mfma_f32_16x16x32_bf16 v[54:57], v[142:145], v[228:231], v[54:57]
	v_mfma_f32_16x16x32_bf16 v[42:45], v[126:129], v[236:239], v[42:45]
	v_mfma_f32_16x16x32_bf16 v[38:41], v[142:145], v[236:239], v[38:41]
	v_mfma_f32_16x16x32_bf16 v[22:25], v[126:129], v[244:247], v[22:25]
	v_mfma_f32_16x16x32_bf16 v[18:21], v[142:145], v[244:247], v[18:21]
	v_mfma_f32_16x16x32_bf16 v[74:77], v[130:133], v[224:227], v[74:77]
	v_mfma_f32_16x16x32_bf16 v[70:73], v[146:149], v[224:227], v[70:73]
	v_mfma_f32_16x16x32_bf16 v[58:61], v[130:133], v[232:235], v[58:61]
	v_mfma_f32_16x16x32_bf16 v[54:57], v[146:149], v[232:235], v[54:57]
	v_mfma_f32_16x16x32_bf16 v[42:45], v[130:133], v[240:243], v[42:45]
	v_mfma_f32_16x16x32_bf16 v[38:41], v[146:149], v[240:243], v[38:41]
	v_mfma_f32_16x16x32_bf16 v[22:25], v[130:133], v[248:251], v[22:25]
	v_mfma_f32_16x16x32_bf16 v[18:21], v[146:149], v[248:251], v[18:21]
	v_mfma_f32_16x16x32_bf16 v[50:53], v[166:169], v[220:223], v[50:53]
	v_mfma_f32_16x16x32_bf16 v[46:49], v[208:211], v[220:223], v[46:49]
	v_mfma_f32_16x16x32_bf16 v[34:37], v[166:169], v[228:231], v[34:37]
	v_mfma_f32_16x16x32_bf16 v[30:33], v[208:211], v[228:231], v[30:33]
	v_mfma_f32_16x16x32_bf16 v[26:29], v[166:169], v[236:239], v[26:29]
	v_mfma_f32_16x16x32_bf16 v[2:5], v[208:211], v[236:239], v[2:5]
	v_mfma_f32_16x16x32_bf16 v[10:13], v[166:169], v[244:247], v[12:15]
	v_mfma_f32_16x16x32_bf16 v[6:9], v[208:211], v[244:247], v[6:9]
	v_mfma_f32_16x16x32_bf16 v[50:53], v[204:207], v[224:227], v[50:53]
	v_mfma_f32_16x16x32_bf16 v[46:49], v[216:219], v[224:227], v[46:49]
	v_mfma_f32_16x16x32_bf16 v[34:37], v[204:207], v[232:235], v[34:37]
	v_mfma_f32_16x16x32_bf16 v[30:33], v[216:219], v[232:235], v[30:33]
	v_mfma_f32_16x16x32_bf16 v[26:29], v[204:207], v[240:243], v[26:29]
	v_mfma_f32_16x16x32_bf16 v[2:5], v[216:219], v[240:243], v[2:5]
	v_mfma_f32_16x16x32_bf16 v[12:15], v[204:207], v[248:251], v[10:13]
	v_mfma_f32_16x16x32_bf16 v[8:11], v[216:219], v[248:251], v[6:9]
	s_barrier
	s_add_i32 s51, s51, 2
	s_add_u32 s18, s18, 0x100
	s_addc_u32 s19, s19, 0
	s_add_u32 s29, s29, 0x100
	s_addc_u32 s50, s50, 0
	s_cmp_gt_u32 s51, 29
	s_cbranch_scc0 .LBB0_164
	s_and_b64 vcc, exec, s[10:11]
	s_cbranch_vccz .LBB0_167
	s_barrier

.LBB0_756:
	s_add_u32 s44, s42, 0xfff80080
	s_addc_u32 s45, s43, -1
	s_add_i32 s62, 0, 0x10000
	s_cmp_eq_u32 s61, 28
	s_cselect_b32 s47, s1, s45
	s_cselect_b32 s46, s21, s44
	v_add_u32_e32 v146, s62, v148
	s_cselect_b32 s45, s19, s51
	s_cselect_b32 s44, s27, s29
	s_add_i32 s64, 0, 0x14000
	ds_read_b128 v[138:141], v146
	ds_read_b128 v[142:145], v146 offset:1024
	ds_read_b128 v[154:157], v146 offset:2048
	ds_read_b128 v[158:161], v146 offset:3072
	v_add_u32_e32 v146, s64, v148
	ds_read_b128 v[162:165], v146
	ds_read_b128 v[166:169], v146 offset:1024
	ds_read_b128 v[170:173], v146 offset:2048
	ds_read_b128 v[174:177], v146 offset:3072
	v_lshl_add_u64 v[146:147], s[42:43], 0, v[134:135]
	s_add_i32 m0, s50, 0xc000
	ds_read_b128 v[178:181], v152
	ds_read_b128 v[182:185], v152 offset:1024
	ds_read_b128 v[186:189], v152 offset:2048
	ds_read_b128 v[190:193], v152 offset:3072
	ds_read_b128 v[194:197], v152 offset:4096
	ds_read_b128 v[198:201], v152 offset:5120
	ds_read_b128 v[202:205], v152 offset:6144
	ds_read_b128 v[206:209], v152 offset:7168
	global_load_lds_dwordx4 v[146:147], off
	v_lshl_add_u64 v[146:147], s[42:43], 0, v[136:137]
	s_add_i32 m0, s50, 0xe000
	s_nop 0
	global_load_lds_dwordx4 v[146:147], off
	s_waitcnt vmcnt(8)
	s_waitcnt lgkmcnt(0)
	s_barrier
	v_mfma_f32_16x16x32_bf16 v[130:133], v[138:141], v[178:181], v[130:133]
	v_mfma_f32_16x16x32_bf16 v[126:129], v[154:157], v[178:181], v[126:129]
	v_mfma_f32_16x16x32_bf16 v[114:117], v[138:141], v[186:189], v[114:117]
	v_mfma_f32_16x16x32_bf16 v[110:113], v[154:157], v[186:189], v[110:113]
	v_mfma_f32_16x16x32_bf16 v[98:101], v[138:141], v[194:197], v[98:101]
	v_mfma_f32_16x16x32_bf16 v[94:97], v[154:157], v[194:197], v[94:97]
	v_mfma_f32_16x16x32_bf16 v[82:85], v[138:141], v[202:205], v[82:85]
	v_mfma_f32_16x16x32_bf16 v[78:81], v[154:157], v[202:205], v[78:81]
	v_mfma_f32_16x16x32_bf16 v[130:133], v[142:145], v[182:185], v[130:133]
	v_mfma_f32_16x16x32_bf16 v[126:129], v[158:161], v[182:185], v[126:129]
	v_mfma_f32_16x16x32_bf16 v[114:117], v[142:145], v[190:193], v[114:117]
	v_mfma_f32_16x16x32_bf16 v[110:113], v[158:161], v[190:193], v[110:113]
	v_mfma_f32_16x16x32_bf16 v[98:101], v[142:145], v[198:201], v[98:101]
	v_mfma_f32_16x16x32_bf16 v[94:97], v[158:161], v[198:201], v[94:97]
	v_mfma_f32_16x16x32_bf16 v[82:85], v[142:145], v[206:209], v[82:85]
	v_mfma_f32_16x16x32_bf16 v[78:81], v[158:161], v[206:209], v[78:81]
	v_mfma_f32_16x16x32_bf16 v[122:125], v[162:165], v[178:181], v[122:125]
	v_mfma_f32_16x16x32_bf16 v[118:121], v[170:173], v[178:181], v[118:121]
	v_mfma_f32_16x16x32_bf16 v[106:109], v[162:165], v[186:189], v[106:109]
	v_mfma_f32_16x16x32_bf16 v[102:105], v[170:173], v[186:189], v[102:105]
	v_mfma_f32_16x16x32_bf16 v[90:93], v[162:165], v[194:197], v[90:93]
	v_mfma_f32_16x16x32_bf16 v[86:89], v[170:173], v[194:197], v[86:89]
	v_mfma_f32_16x16x32_bf16 v[74:77], v[162:165], v[202:205], v[74:77]
	v_mfma_f32_16x16x32_bf16 v[70:73], v[170:173], v[202:205], v[70:73]
	v_mfma_f32_16x16x32_bf16 v[122:125], v[166:169], v[182:185], v[122:125]
	v_mfma_f32_16x16x32_bf16 v[118:121], v[174:177], v[182:185], v[118:121]
	v_mfma_f32_16x16x32_bf16 v[106:109], v[166:169], v[190:193], v[106:109]
	v_mfma_f32_16x16x32_bf16 v[102:105], v[174:177], v[190:193], v[102:105]
	v_mfma_f32_16x16x32_bf16 v[90:93], v[166:169], v[198:201], v[90:93]
	v_mfma_f32_16x16x32_bf16 v[86:89], v[174:177], v[198:201], v[86:89]
	v_mfma_f32_16x16x32_bf16 v[74:77], v[166:169], v[206:209], v[74:77]
	v_mfma_f32_16x16x32_bf16 v[70:73], v[174:177], v[206:209], v[70:73]
	s_barrier
	s_add_i32 s62, s62, s33
	v_lshl_add_u64 v[146:147], s[44:45], 0, v[0:1]
	s_mov_b32 m0, s62
	ds_read_b128 v[178:181], v152 offset:16384
	ds_read_b128 v[182:185], v152 offset:17408
	ds_read_b128 v[186:189], v152 offset:18432
	ds_read_b128 v[190:193], v152 offset:19456
	ds_read_b128 v[194:197], v152 offset:20480
	ds_read_b128 v[198:201], v152 offset:21504
	ds_read_b128 v[202:205], v152 offset:22528
	ds_read_b128 v[206:209], v152 offset:23552
	global_load_lds_dwordx4 v[146:147], off
	s_add_i32 m0, s62, 0x2000
	s_add_u32 s62, s44, 0x80000
	v_lshl_add_u64 v[210:211], s[44:45], 0, v[14:15]
	s_addc_u32 s63, s45, 0
	s_add_i32 s64, s64, s33
	global_load_lds_dwordx4 v[210:211], off
	v_lshl_add_u64 v[212:213], s[62:63], 0, v[0:1]
	s_mov_b32 m0, s64
	v_lshl_add_u64 v[214:215], s[46:47], 0, v[14:15]
	global_load_lds_dwordx4 v[212:213], off
	v_lshl_add_u64 v[212:213], s[62:63], 0, v[14:15]
	s_add_i32 m0, s64, 0x2000
	s_nop 0
	global_load_lds_dwordx4 v[212:213], off
	v_lshl_add_u64 v[212:213], s[46:47], 0, v[0:1]
	s_mov_b32 m0, s50
	s_nop 0
	global_load_lds_dwordx4 v[212:213], off
	s_mov_b32 m0, s52
	s_nop 0
	global_load_lds_dwordx4 v[214:215], off
	s_waitcnt vmcnt(8)
	s_waitcnt lgkmcnt(0)
	s_barrier
	v_mfma_f32_16x16x32_bf16 v[66:69], v[138:141], v[178:181], v[66:69]
	v_mfma_f32_16x16x32_bf16 v[62:65], v[154:157], v[178:181], v[62:65]
	v_mfma_f32_16x16x32_bf16 v[50:53], v[138:141], v[186:189], v[50:53]
	v_mfma_f32_16x16x32_bf16 v[46:49], v[154:157], v[186:189], v[46:49]
	v_mfma_f32_16x16x32_bf16 v[34:37], v[138:141], v[194:197], v[34:37]
	v_mfma_f32_16x16x32_bf16 v[30:33], v[154:157], v[194:197], v[30:33]
	v_mfma_f32_16x16x32_bf16 v[18:21], v[138:141], v[202:205], v[18:21]
	v_mfma_f32_16x16x32_bf16 v[10:13], v[154:157], v[202:205], v[10:13]
	v_mfma_f32_16x16x32_bf16 v[66:69], v[142:145], v[182:185], v[66:69]
	v_mfma_f32_16x16x32_bf16 v[62:65], v[158:161], v[182:185], v[62:65]
	v_mfma_f32_16x16x32_bf16 v[50:53], v[142:145], v[190:193], v[50:53]
	v_mfma_f32_16x16x32_bf16 v[46:49], v[158:161], v[190:193], v[46:49]
	v_mfma_f32_16x16x32_bf16 v[34:37], v[142:145], v[198:201], v[34:37]
	v_mfma_f32_16x16x32_bf16 v[30:33], v[158:161], v[198:201], v[30:33]
	v_mfma_f32_16x16x32_bf16 v[18:21], v[142:145], v[206:209], v[18:21]
	v_mfma_f32_16x16x32_bf16 v[10:13], v[158:161], v[206:209], v[10:13]
	v_mfma_f32_16x16x32_bf16 v[58:61], v[162:165], v[178:181], v[58:61]
	v_mfma_f32_16x16x32_bf16 v[54:57], v[170:173], v[178:181], v[54:57]
	v_mfma_f32_16x16x32_bf16 v[42:45], v[162:165], v[186:189], v[42:45]
	v_mfma_f32_16x16x32_bf16 v[38:41], v[170:173], v[186:189], v[38:41]
	v_mfma_f32_16x16x32_bf16 v[26:29], v[162:165], v[194:197], v[26:29]
	v_mfma_f32_16x16x32_bf16 v[22:25], v[170:173], v[194:197], v[22:25]
	v_mfma_f32_16x16x32_bf16 v[6:9], v[162:165], v[202:205], v[6:9]
	v_mfma_f32_16x16x32_bf16 v[2:5], v[170:173], v[202:205], v[2:5]
	v_mfma_f32_16x16x32_bf16 v[58:61], v[166:169], v[182:185], v[58:61]
	v_mfma_f32_16x16x32_bf16 v[54:57], v[174:177], v[182:185], v[54:57]
	v_mfma_f32_16x16x32_bf16 v[42:45], v[166:169], v[190:193], v[42:45]
	v_mfma_f32_16x16x32_bf16 v[38:41], v[174:177], v[190:193], v[38:41]
	v_mfma_f32_16x16x32_bf16 v[26:29], v[166:169], v[198:201], v[26:29]
	v_mfma_f32_16x16x32_bf16 v[22:25], v[174:177], v[198:201], v[22:25]
	v_mfma_f32_16x16x32_bf16 v[6:9], v[166:169], v[206:209], v[6:9]
	v_mfma_f32_16x16x32_bf16 v[2:5], v[174:177], v[206:209], v[2:5]
	s_barrier
	s_add_i32 s62, 0, 0x18000
	s_add_i32 s63, 0, 0x1c000
	v_add_u32_e32 v158, s62, v148
	v_add_u32_e32 v174, s63, v148
	ds_read_b128 v[138:141], v158
	ds_read_b128 v[142:145], v158 offset:1024
	ds_read_b128 v[154:157], v158 offset:2048
	ds_read_b128 v[158:161], v158 offset:3072
	ds_read_b128 v[162:165], v174
	ds_read_b128 v[166:169], v174 offset:1024
	ds_read_b128 v[170:173], v174 offset:2048
	ds_read_b128 v[174:177], v174 offset:3072
	s_add_u32 s46, s46, 0x80000
	s_addc_u32 s47, s47, 0
	s_mov_b32 m0, s53
	v_lshl_add_u64 v[216:217], s[46:47], 0, v[0:1]
	ds_read_b128 v[178:181], v152 offset:32768
	ds_read_b128 v[182:185], v152 offset:33792
	ds_read_b128 v[186:189], v152 offset:34816
	ds_read_b128 v[190:193], v152 offset:35840
	ds_read_b128 v[194:197], v152 offset:36864
	ds_read_b128 v[198:201], v152 offset:37888
	ds_read_b128 v[202:205], v152 offset:38912
	ds_read_b128 v[206:209], v152 offset:39936
	global_load_lds_dwordx4 v[216:217], off
	v_lshl_add_u64 v[216:217], s[46:47], 0, v[14:15]
	s_mov_b32 m0, s54
	s_nop 0
	global_load_lds_dwordx4 v[216:217], off
	s_waitcnt vmcnt(8)
	s_waitcnt lgkmcnt(0)
	s_barrier
	v_mfma_f32_16x16x32_bf16 v[130:133], v[138:141], v[178:181], v[130:133]
	v_mfma_f32_16x16x32_bf16 v[126:129], v[154:157], v[178:181], v[126:129]
	v_mfma_f32_16x16x32_bf16 v[114:117], v[138:141], v[186:189], v[114:117]
	v_mfma_f32_16x16x32_bf16 v[110:113], v[154:157], v[186:189], v[110:113]
	v_mfma_f32_16x16x32_bf16 v[98:101], v[138:141], v[194:197], v[98:101]
	v_mfma_f32_16x16x32_bf16 v[94:97], v[154:157], v[194:197], v[94:97]
	v_mfma_f32_16x16x32_bf16 v[82:85], v[138:141], v[202:205], v[82:85]
	v_mfma_f32_16x16x32_bf16 v[78:81], v[154:157], v[202:205], v[78:81]
	v_mfma_f32_16x16x32_bf16 v[130:133], v[142:145], v[182:185], v[130:133]
	v_mfma_f32_16x16x32_bf16 v[126:129], v[158:161], v[182:185], v[126:129]
	v_mfma_f32_16x16x32_bf16 v[114:117], v[142:145], v[190:193], v[114:117]
	v_mfma_f32_16x16x32_bf16 v[110:113], v[158:161], v[190:193], v[110:113]
	v_mfma_f32_16x16x32_bf16 v[98:101], v[142:145], v[198:201], v[98:101]
	v_mfma_f32_16x16x32_bf16 v[94:97], v[158:161], v[198:201], v[94:97]
	v_mfma_f32_16x16x32_bf16 v[82:85], v[142:145], v[206:209], v[82:85]
	v_mfma_f32_16x16x32_bf16 v[78:81], v[158:161], v[206:209], v[78:81]
	v_mfma_f32_16x16x32_bf16 v[122:125], v[162:165], v[178:181], v[122:125]
	v_mfma_f32_16x16x32_bf16 v[118:121], v[170:173], v[178:181], v[118:121]
	v_mfma_f32_16x16x32_bf16 v[106:109], v[162:165], v[186:189], v[106:109]
	v_mfma_f32_16x16x32_bf16 v[102:105], v[170:173], v[186:189], v[102:105]
	v_mfma_f32_16x16x32_bf16 v[90:93], v[162:165], v[194:197], v[90:93]
	v_mfma_f32_16x16x32_bf16 v[86:89], v[170:173], v[194:197], v[86:89]
	v_mfma_f32_16x16x32_bf16 v[74:77], v[162:165], v[202:205], v[74:77]
	v_mfma_f32_16x16x32_bf16 v[70:73], v[170:173], v[202:205], v[70:73]
	v_mfma_f32_16x16x32_bf16 v[122:125], v[166:169], v[182:185], v[122:125]
	v_mfma_f32_16x16x32_bf16 v[118:121], v[174:177], v[182:185], v[118:121]
	v_mfma_f32_16x16x32_bf16 v[106:109], v[166:169], v[190:193], v[106:109]
	v_mfma_f32_16x16x32_bf16 v[102:105], v[174:177], v[190:193], v[102:105]
	v_mfma_f32_16x16x32_bf16 v[90:93], v[166:169], v[198:201], v[90:93]
	v_mfma_f32_16x16x32_bf16 v[86:89], v[174:177], v[198:201], v[86:89]
	v_mfma_f32_16x16x32_bf16 v[74:77], v[166:169], v[206:209], v[74:77]
	v_mfma_f32_16x16x32_bf16 v[70:73], v[174:177], v[206:209], v[70:73]
	s_barrier
	s_add_i32 s46, s62, s33
	v_lshl_add_u64 v[146:147], v[146:147], 0, s[36:37]
	s_mov_b32 m0, s46
	ds_read_b128 v[178:181], v152 offset:49152
	ds_read_b128 v[182:185], v152 offset:50176
	ds_read_b128 v[186:189], v152 offset:51200
	ds_read_b128 v[190:193], v152 offset:52224
	ds_read_b128 v[194:197], v152 offset:53248
	ds_read_b128 v[198:201], v152 offset:54272
	ds_read_b128 v[202:205], v152 offset:55296
	ds_read_b128 v[206:209], v152 offset:56320
	global_load_lds_dwordx4 v[146:147], off
	s_add_i32 m0, s46, 0x2000
	s_add_u32 s44, s44, 0x80080
	v_lshl_add_u64 v[146:147], v[210:211], 0, s[36:37]
	s_addc_u32 s45, s45, 0
	s_add_i32 s46, s63, s33
	global_load_lds_dwordx4 v[146:147], off
	v_lshl_add_u64 v[146:147], s[44:45], 0, v[0:1]
	s_mov_b32 m0, s46
	s_nop 0
	global_load_lds_dwordx4 v[146:147], off
	v_lshl_add_u64 v[146:147], s[44:45], 0, v[14:15]
	s_add_i32 m0, s46, 0x2000
	s_nop 0
	global_load_lds_dwordx4 v[146:147], off
	v_lshl_add_u64 v[146:147], v[212:213], 0, s[36:37]
	s_mov_b32 m0, s56
	s_nop 0
	global_load_lds_dwordx4 v[146:147], off
	v_lshl_add_u64 v[146:147], v[214:215], 0, s[36:37]
	s_mov_b32 m0, s57
	s_nop 0
	global_load_lds_dwordx4 v[146:147], off
	s_waitcnt vmcnt(8)
	s_waitcnt lgkmcnt(0)
	s_barrier
	v_mfma_f32_16x16x32_bf16 v[66:69], v[138:141], v[178:181], v[66:69]
	v_mfma_f32_16x16x32_bf16 v[62:65], v[154:157], v[178:181], v[62:65]
	v_mfma_f32_16x16x32_bf16 v[50:53], v[138:141], v[186:189], v[50:53]
	v_mfma_f32_16x16x32_bf16 v[46:49], v[154:157], v[186:189], v[46:49]
	v_mfma_f32_16x16x32_bf16 v[34:37], v[138:141], v[194:197], v[34:37]
	v_mfma_f32_16x16x32_bf16 v[30:33], v[154:157], v[194:197], v[30:33]
	v_mfma_f32_16x16x32_bf16 v[18:21], v[138:141], v[202:205], v[18:21]
	v_mfma_f32_16x16x32_bf16 v[10:13], v[154:157], v[202:205], v[10:13]
	v_mfma_f32_16x16x32_bf16 v[66:69], v[142:145], v[182:185], v[66:69]
	v_mfma_f32_16x16x32_bf16 v[62:65], v[158:161], v[182:185], v[62:65]
	v_mfma_f32_16x16x32_bf16 v[50:53], v[142:145], v[190:193], v[50:53]
	v_mfma_f32_16x16x32_bf16 v[46:49], v[158:161], v[190:193], v[46:49]
	v_mfma_f32_16x16x32_bf16 v[34:37], v[142:145], v[198:201], v[34:37]
	v_mfma_f32_16x16x32_bf16 v[30:33], v[158:161], v[198:201], v[30:33]
	v_mfma_f32_16x16x32_bf16 v[18:21], v[142:145], v[206:209], v[18:21]
	v_mfma_f32_16x16x32_bf16 v[10:13], v[158:161], v[206:209], v[10:13]
	v_mfma_f32_16x16x32_bf16 v[58:61], v[162:165], v[178:181], v[58:61]
	v_mfma_f32_16x16x32_bf16 v[54:57], v[170:173], v[178:181], v[54:57]
	v_mfma_f32_16x16x32_bf16 v[42:45], v[162:165], v[186:189], v[42:45]
	v_mfma_f32_16x16x32_bf16 v[38:41], v[170:173], v[186:189], v[38:41]
	v_mfma_f32_16x16x32_bf16 v[26:29], v[162:165], v[194:197], v[26:29]
	v_mfma_f32_16x16x32_bf16 v[22:25], v[170:173], v[194:197], v[22:25]
	v_mfma_f32_16x16x32_bf16 v[6:9], v[162:165], v[202:205], v[6:9]
	v_mfma_f32_16x16x32_bf16 v[2:5], v[170:173], v[202:205], v[2:5]
	v_mfma_f32_16x16x32_bf16 v[58:61], v[166:169], v[182:185], v[58:61]
	v_mfma_f32_16x16x32_bf16 v[54:57], v[174:177], v[182:185], v[54:57]
	v_mfma_f32_16x16x32_bf16 v[42:45], v[166:169], v[190:193], v[42:45]
	v_mfma_f32_16x16x32_bf16 v[38:41], v[174:177], v[190:193], v[38:41]
	v_mfma_f32_16x16x32_bf16 v[26:29], v[166:169], v[198:201], v[26:29]
	v_mfma_f32_16x16x32_bf16 v[22:25], v[174:177], v[198:201], v[22:25]
	v_mfma_f32_16x16x32_bf16 v[6:9], v[166:169], v[206:209], v[6:9]
	v_mfma_f32_16x16x32_bf16 v[2:5], v[174:177], v[206:209], v[2:5]
	s_barrier
	s_add_i32 s61, s61, 2
	s_add_u32 s42, s42, 0x100
	s_addc_u32 s43, s43, 0
	s_add_u32 s29, s29, 0x100
	s_addc_u32 s51, s51, 0
	s_cmp_gt_u32 s61, 29
	s_cbranch_scc0 .LBB0_756
	s_and_b64 vcc, exec, s[10:11]
	s_cbranch_vccz .LBB0_759
	s_barrier

.LBB0_878:
	s_add_u32 s20, s8, 0xfff80080
	s_addc_u32 s21, s9, -1
	s_add_i32 s53, 0, 0x10000
	s_cmp_eq_u32 s52, 28
	s_cselect_b32 s23, s7, s21
	s_cselect_b32 s22, s25, s20
	v_add_u32_e32 v6, s53, v170
	s_cselect_b32 s21, s5, s51
	s_cselect_b32 s20, s47, s50
	s_add_i32 s54, 0, 0x14000
	ds_read_b128 v[126:129], v6
	ds_read_b128 v[130:133], v6 offset:1024
	ds_read_b128 v[142:145], v6 offset:2048
	ds_read_b128 v[146:149], v6 offset:3072
	v_add_u32_e32 v6, s54, v170
	ds_read_b128 v[164:167], v6
	ds_read_b128 v[204:207], v6 offset:1024
	ds_read_b128 v[208:211], v6 offset:2048
	ds_read_b128 v[216:219], v6 offset:3072
	v_lshl_add_u64 v[6:7], s[8:9], 0, v[160:161]
	s_add_i32 m0, s38, 0xc000
	ds_read_b128 v[220:223], v196
	ds_read_b128 v[224:227], v196 offset:1024
	ds_read_b128 v[228:231], v196 offset:2048
	ds_read_b128 v[232:235], v196 offset:3072
	ds_read_b128 v[236:239], v196 offset:4096
	ds_read_b128 v[240:243], v196 offset:5120
	ds_read_b128 v[244:247], v196 offset:6144
	ds_read_b128 v[248:251], v196 offset:7168
	global_load_lds_dwordx4 v[6:7], off
	v_lshl_add_u64 v[6:7], s[8:9], 0, v[162:163]
	s_add_i32 m0, s38, 0xe000
	s_nop 0
	global_load_lds_dwordx4 v[6:7], off
	s_waitcnt vmcnt(8)
	s_waitcnt lgkmcnt(0)
	s_barrier
	v_mfma_f32_16x16x32_bf16 v[138:141], v[126:129], v[220:223], v[138:141]
	v_mfma_f32_16x16x32_bf16 v[134:137], v[142:145], v[220:223], v[134:137]
	v_mfma_f32_16x16x32_bf16 v[122:125], v[126:129], v[228:231], v[122:125]
	v_mfma_f32_16x16x32_bf16 v[118:121], v[142:145], v[228:231], v[118:121]
	v_mfma_f32_16x16x32_bf16 v[106:109], v[126:129], v[236:239], v[106:109]
	v_mfma_f32_16x16x32_bf16 v[102:105], v[142:145], v[236:239], v[102:105]
	v_mfma_f32_16x16x32_bf16 v[90:93], v[126:129], v[244:247], v[90:93]
	v_mfma_f32_16x16x32_bf16 v[86:89], v[142:145], v[244:247], v[86:89]
	v_mfma_f32_16x16x32_bf16 v[138:141], v[130:133], v[224:227], v[138:141]
	v_mfma_f32_16x16x32_bf16 v[134:137], v[146:149], v[224:227], v[134:137]
	v_mfma_f32_16x16x32_bf16 v[122:125], v[130:133], v[232:235], v[122:125]
	v_mfma_f32_16x16x32_bf16 v[118:121], v[146:149], v[232:235], v[118:121]
	v_mfma_f32_16x16x32_bf16 v[106:109], v[130:133], v[240:243], v[106:109]
	v_mfma_f32_16x16x32_bf16 v[102:105], v[146:149], v[240:243], v[102:105]
	v_mfma_f32_16x16x32_bf16 v[90:93], v[130:133], v[248:251], v[90:93]
	v_mfma_f32_16x16x32_bf16 v[86:89], v[146:149], v[248:251], v[86:89]
	v_mfma_f32_16x16x32_bf16 v[114:117], v[164:167], v[220:223], v[114:117]
	v_mfma_f32_16x16x32_bf16 v[110:113], v[208:211], v[220:223], v[110:113]
	v_mfma_f32_16x16x32_bf16 v[98:101], v[164:167], v[228:231], v[98:101]
	v_mfma_f32_16x16x32_bf16 v[94:97], v[208:211], v[228:231], v[94:97]
	v_mfma_f32_16x16x32_bf16 v[82:85], v[164:167], v[236:239], v[82:85]
	v_mfma_f32_16x16x32_bf16 v[78:81], v[208:211], v[236:239], v[78:81]
	v_mfma_f32_16x16x32_bf16 v[66:69], v[164:167], v[244:247], v[66:69]
	v_mfma_f32_16x16x32_bf16 v[62:65], v[208:211], v[244:247], v[62:65]
	v_mfma_f32_16x16x32_bf16 v[114:117], v[204:207], v[224:227], v[114:117]
	v_mfma_f32_16x16x32_bf16 v[110:113], v[216:219], v[224:227], v[110:113]
	v_mfma_f32_16x16x32_bf16 v[98:101], v[204:207], v[232:235], v[98:101]
	v_mfma_f32_16x16x32_bf16 v[94:97], v[216:219], v[232:235], v[94:97]
	v_mfma_f32_16x16x32_bf16 v[82:85], v[204:207], v[240:243], v[82:85]
	v_mfma_f32_16x16x32_bf16 v[78:81], v[216:219], v[240:243], v[78:81]
	v_mfma_f32_16x16x32_bf16 v[66:69], v[204:207], v[248:251], v[66:69]
	v_mfma_f32_16x16x32_bf16 v[62:65], v[216:219], v[248:251], v[62:65]
	s_barrier
	s_add_i32 s53, s53, s17
	v_lshl_add_u64 v[168:169], s[20:21], 0, v[0:1]
	s_mov_b32 m0, s53
	ds_read_b128 v[220:223], v196 offset:16384
	ds_read_b128 v[224:227], v196 offset:17408
	ds_read_b128 v[228:231], v196 offset:18432
	ds_read_b128 v[232:235], v196 offset:19456
	ds_read_b128 v[236:239], v196 offset:20480
	ds_read_b128 v[240:243], v196 offset:21504
	ds_read_b128 v[244:247], v196 offset:22528
	ds_read_b128 v[248:251], v196 offset:23552
	global_load_lds_dwordx4 v[168:169], off
	s_add_i32 m0, s53, 0x2000
	s_add_u32 s56, s20, 0x80000
	v_lshl_add_u64 v[198:199], s[20:21], 0, v[154:155]
	s_addc_u32 s57, s21, 0
	s_add_i32 s53, s54, s17
	global_load_lds_dwordx4 v[198:199], off
	v_lshl_add_u64 v[6:7], s[56:57], 0, v[0:1]
	s_mov_b32 m0, s53
	v_lshl_add_u64 v[200:201], s[22:23], 0, v[150:151]
	global_load_lds_dwordx4 v[6:7], off
	v_lshl_add_u64 v[6:7], s[56:57], 0, v[154:155]
	s_add_i32 m0, s53, 0x2000
	v_lshl_add_u64 v[202:203], s[22:23], 0, v[152:153]
	global_load_lds_dwordx4 v[6:7], off
	s_mov_b32 m0, s38
	s_nop 0
	global_load_lds_dwordx4 v[200:201], off
	s_mov_b32 m0, s39
	s_nop 0
	global_load_lds_dwordx4 v[202:203], off
	s_waitcnt vmcnt(8)
	s_waitcnt lgkmcnt(0)
	s_barrier
	v_mfma_f32_16x16x32_bf16 v[74:77], v[126:129], v[220:223], v[74:77]
	v_mfma_f32_16x16x32_bf16 v[70:73], v[142:145], v[220:223], v[70:73]
	v_mfma_f32_16x16x32_bf16 v[58:61], v[126:129], v[228:231], v[58:61]
	v_mfma_f32_16x16x32_bf16 v[54:57], v[142:145], v[228:231], v[54:57]
	v_mfma_f32_16x16x32_bf16 v[42:45], v[126:129], v[236:239], v[42:45]
	v_mfma_f32_16x16x32_bf16 v[38:41], v[142:145], v[236:239], v[38:41]
	v_mfma_f32_16x16x32_bf16 v[22:25], v[126:129], v[244:247], v[22:25]
	v_mfma_f32_16x16x32_bf16 v[18:21], v[142:145], v[244:247], v[18:21]
	v_mfma_f32_16x16x32_bf16 v[74:77], v[130:133], v[224:227], v[74:77]
	v_mfma_f32_16x16x32_bf16 v[70:73], v[146:149], v[224:227], v[70:73]
	v_mfma_f32_16x16x32_bf16 v[58:61], v[130:133], v[232:235], v[58:61]
	v_mfma_f32_16x16x32_bf16 v[54:57], v[146:149], v[232:235], v[54:57]
	v_mfma_f32_16x16x32_bf16 v[42:45], v[130:133], v[240:243], v[42:45]
	v_mfma_f32_16x16x32_bf16 v[38:41], v[146:149], v[240:243], v[38:41]
	v_mfma_f32_16x16x32_bf16 v[22:25], v[130:133], v[248:251], v[22:25]
	v_mfma_f32_16x16x32_bf16 v[18:21], v[146:149], v[248:251], v[18:21]
	v_mfma_f32_16x16x32_bf16 v[50:53], v[164:167], v[220:223], v[50:53]
	v_mfma_f32_16x16x32_bf16 v[46:49], v[208:211], v[220:223], v[46:49]
	v_mfma_f32_16x16x32_bf16 v[34:37], v[164:167], v[228:231], v[34:37]
	v_mfma_f32_16x16x32_bf16 v[30:33], v[208:211], v[228:231], v[30:33]
	v_mfma_f32_16x16x32_bf16 v[26:29], v[164:167], v[236:239], v[26:29]
	v_mfma_f32_16x16x32_bf16 v[2:5], v[208:211], v[236:239], v[2:5]
	v_mfma_f32_16x16x32_bf16 v[12:15], v[164:167], v[244:247], v[12:15]
	v_mfma_f32_16x16x32_bf16 v[6:9], v[208:211], v[244:247], v[8:11]
	v_mfma_f32_16x16x32_bf16 v[50:53], v[204:207], v[224:227], v[50:53]
	v_mfma_f32_16x16x32_bf16 v[46:49], v[216:219], v[224:227], v[46:49]
	v_mfma_f32_16x16x32_bf16 v[34:37], v[204:207], v[232:235], v[34:37]
	v_mfma_f32_16x16x32_bf16 v[30:33], v[216:219], v[232:235], v[30:33]
	v_mfma_f32_16x16x32_bf16 v[26:29], v[204:207], v[240:243], v[26:29]
	v_mfma_f32_16x16x32_bf16 v[2:5], v[216:219], v[240:243], v[2:5]
	v_mfma_f32_16x16x32_bf16 v[12:15], v[204:207], v[248:251], v[12:15]
	v_mfma_f32_16x16x32_bf16 v[6:9], v[216:219], v[248:251], v[6:9]
	s_barrier
	s_add_i32 s53, 0, 0x18000
	v_add_u32_e32 v10, s53, v170
	s_add_i32 s54, 0, 0x1c000
	ds_read_b128 v[126:129], v10
	ds_read_b128 v[130:133], v10 offset:1024
	ds_read_b128 v[142:145], v10 offset:2048
	ds_read_b128 v[146:149], v10 offset:3072
	v_add_u32_e32 v10, s54, v170
	ds_read_b128 v[164:167], v10
	ds_read_b128 v[204:207], v10 offset:1024
	ds_read_b128 v[208:211], v10 offset:2048
	ds_read_b128 v[216:219], v10 offset:3072
	s_add_u32 s22, s22, 0x80000
	s_addc_u32 s23, s23, 0
	s_mov_b32 m0, s40
	v_lshl_add_u64 v[10:11], s[22:23], 0, v[150:151]
	ds_read_b128 v[220:223], v196 offset:32768
	ds_read_b128 v[224:227], v196 offset:33792
	ds_read_b128 v[228:231], v196 offset:34816
	ds_read_b128 v[232:235], v196 offset:35840
	ds_read_b128 v[236:239], v196 offset:36864
	ds_read_b128 v[240:243], v196 offset:37888
	ds_read_b128 v[244:247], v196 offset:38912
	ds_read_b128 v[248:251], v196 offset:39936
	global_load_lds_dwordx4 v[10:11], off
	v_lshl_add_u64 v[10:11], s[22:23], 0, v[152:153]
	s_mov_b32 m0, s41
	s_nop 0
	global_load_lds_dwordx4 v[10:11], off
	s_waitcnt vmcnt(8)
	s_waitcnt lgkmcnt(0)
	s_barrier
	v_mfma_f32_16x16x32_bf16 v[138:141], v[126:129], v[220:223], v[138:141]
	v_mfma_f32_16x16x32_bf16 v[134:137], v[142:145], v[220:223], v[134:137]
	v_mfma_f32_16x16x32_bf16 v[122:125], v[126:129], v[228:231], v[122:125]
	v_mfma_f32_16x16x32_bf16 v[118:121], v[142:145], v[228:231], v[118:121]
	v_mfma_f32_16x16x32_bf16 v[106:109], v[126:129], v[236:239], v[106:109]
	v_mfma_f32_16x16x32_bf16 v[102:105], v[142:145], v[236:239], v[102:105]
	v_mfma_f32_16x16x32_bf16 v[90:93], v[126:129], v[244:247], v[90:93]
	v_mfma_f32_16x16x32_bf16 v[86:89], v[142:145], v[244:247], v[86:89]
	v_mfma_f32_16x16x32_bf16 v[138:141], v[130:133], v[224:227], v[138:141]
	v_mfma_f32_16x16x32_bf16 v[134:137], v[146:149], v[224:227], v[134:137]
	v_mfma_f32_16x16x32_bf16 v[122:125], v[130:133], v[232:235], v[122:125]
	v_mfma_f32_16x16x32_bf16 v[118:121], v[146:149], v[232:235], v[118:121]
	v_mfma_f32_16x16x32_bf16 v[106:109], v[130:133], v[240:243], v[106:109]
	v_mfma_f32_16x16x32_bf16 v[102:105], v[146:149], v[240:243], v[102:105]
	v_mfma_f32_16x16x32_bf16 v[90:93], v[130:133], v[248:251], v[90:93]
	v_mfma_f32_16x16x32_bf16 v[86:89], v[146:149], v[248:251], v[86:89]
	v_mfma_f32_16x16x32_bf16 v[114:117], v[164:167], v[220:223], v[114:117]
	v_mfma_f32_16x16x32_bf16 v[110:113], v[208:211], v[220:223], v[110:113]
	v_mfma_f32_16x16x32_bf16 v[98:101], v[164:167], v[228:231], v[98:101]
	v_mfma_f32_16x16x32_bf16 v[94:97], v[208:211], v[228:231], v[94:97]
	v_mfma_f32_16x16x32_bf16 v[82:85], v[164:167], v[236:239], v[82:85]
	v_mfma_f32_16x16x32_bf16 v[78:81], v[208:211], v[236:239], v[78:81]
	v_mfma_f32_16x16x32_bf16 v[66:69], v[164:167], v[244:247], v[66:69]
	v_mfma_f32_16x16x32_bf16 v[62:65], v[208:211], v[244:247], v[62:65]
	v_mfma_f32_16x16x32_bf16 v[114:117], v[204:207], v[224:227], v[114:117]
	v_mfma_f32_16x16x32_bf16 v[110:113], v[216:219], v[224:227], v[110:113]
	v_mfma_f32_16x16x32_bf16 v[98:101], v[204:207], v[232:235], v[98:101]
	v_mfma_f32_16x16x32_bf16 v[94:97], v[216:219], v[232:235], v[94:97]
	v_mfma_f32_16x16x32_bf16 v[82:85], v[204:207], v[240:243], v[82:85]
	v_mfma_f32_16x16x32_bf16 v[78:81], v[216:219], v[240:243], v[78:81]
	v_mfma_f32_16x16x32_bf16 v[66:69], v[204:207], v[248:251], v[66:69]
	v_mfma_f32_16x16x32_bf16 v[62:65], v[216:219], v[248:251], v[62:65]
	s_barrier
	s_add_i32 s22, s53, s17
	v_lshl_add_u64 v[10:11], v[168:169], 0, s[36:37]
	s_mov_b32 m0, s22
	ds_read_b128 v[220:223], v196 offset:49152
	ds_read_b128 v[224:227], v196 offset:50176
	ds_read_b128 v[228:231], v196 offset:51200
	ds_read_b128 v[232:235], v196 offset:52224
	ds_read_b128 v[236:239], v196 offset:53248
	ds_read_b128 v[240:243], v196 offset:54272
	ds_read_b128 v[244:247], v196 offset:55296
	ds_read_b128 v[248:251], v196 offset:56320
	global_load_lds_dwordx4 v[10:11], off
	s_add_i32 m0, s22, 0x2000
	s_add_u32 s20, s20, 0x80080
	v_lshl_add_u64 v[10:11], v[198:199], 0, s[36:37]
	s_addc_u32 s21, s21, 0
	s_add_i32 s22, s54, s17
	global_load_lds_dwordx4 v[10:11], off
	v_lshl_add_u64 v[10:11], s[20:21], 0, v[0:1]
	s_mov_b32 m0, s22
	s_nop 0
	global_load_lds_dwordx4 v[10:11], off
	v_lshl_add_u64 v[10:11], s[20:21], 0, v[154:155]
	s_add_i32 m0, s22, 0x2000
	s_nop 0
	global_load_lds_dwordx4 v[10:11], off
	v_lshl_add_u64 v[10:11], v[200:201], 0, s[36:37]
	s_mov_b32 m0, s2
	s_nop 0
	global_load_lds_dwordx4 v[10:11], off
	v_lshl_add_u64 v[10:11], v[202:203], 0, s[36:37]
	s_mov_b32 m0, s3
	s_nop 0
	global_load_lds_dwordx4 v[10:11], off
	s_waitcnt vmcnt(8)
	s_waitcnt lgkmcnt(0)
	s_barrier
	v_mfma_f32_16x16x32_bf16 v[74:77], v[126:129], v[220:223], v[74:77]
	v_mfma_f32_16x16x32_bf16 v[70:73], v[142:145], v[220:223], v[70:73]
	v_mfma_f32_16x16x32_bf16 v[58:61], v[126:129], v[228:231], v[58:61]
	v_mfma_f32_16x16x32_bf16 v[54:57], v[142:145], v[228:231], v[54:57]
	v_mfma_f32_16x16x32_bf16 v[42:45], v[126:129], v[236:239], v[42:45]
	v_mfma_f32_16x16x32_bf16 v[38:41], v[142:145], v[236:239], v[38:41]
	v_mfma_f32_16x16x32_bf16 v[22:25], v[126:129], v[244:247], v[22:25]
	v_mfma_f32_16x16x32_bf16 v[18:21], v[142:145], v[244:247], v[18:21]
	v_mfma_f32_16x16x32_bf16 v[74:77], v[130:133], v[224:227], v[74:77]
	v_mfma_f32_16x16x32_bf16 v[70:73], v[146:149], v[224:227], v[70:73]
	v_mfma_f32_16x16x32_bf16 v[58:61], v[130:133], v[232:235], v[58:61]
	v_mfma_f32_16x16x32_bf16 v[54:57], v[146:149], v[232:235], v[54:57]
	v_mfma_f32_16x16x32_bf16 v[42:45], v[130:133], v[240:243], v[42:45]
	v_mfma_f32_16x16x32_bf16 v[38:41], v[146:149], v[240:243], v[38:41]
	v_mfma_f32_16x16x32_bf16 v[22:25], v[130:133], v[248:251], v[22:25]
	v_mfma_f32_16x16x32_bf16 v[18:21], v[146:149], v[248:251], v[18:21]
	v_mfma_f32_16x16x32_bf16 v[50:53], v[164:167], v[220:223], v[50:53]
	v_mfma_f32_16x16x32_bf16 v[46:49], v[208:211], v[220:223], v[46:49]
	v_mfma_f32_16x16x32_bf16 v[34:37], v[164:167], v[228:231], v[34:37]
	v_mfma_f32_16x16x32_bf16 v[30:33], v[208:211], v[228:231], v[30:33]
	v_mfma_f32_16x16x32_bf16 v[26:29], v[164:167], v[236:239], v[26:29]
	v_mfma_f32_16x16x32_bf16 v[2:5], v[208:211], v[236:239], v[2:5]
	v_mfma_f32_16x16x32_bf16 v[10:13], v[164:167], v[244:247], v[12:15]
	v_mfma_f32_16x16x32_bf16 v[6:9], v[208:211], v[244:247], v[6:9]
	v_mfma_f32_16x16x32_bf16 v[50:53], v[204:207], v[224:227], v[50:53]
	v_mfma_f32_16x16x32_bf16 v[46:49], v[216:219], v[224:227], v[46:49]
	v_mfma_f32_16x16x32_bf16 v[34:37], v[204:207], v[232:235], v[34:37]
	v_mfma_f32_16x16x32_bf16 v[30:33], v[216:219], v[232:235], v[30:33]
	v_mfma_f32_16x16x32_bf16 v[26:29], v[204:207], v[240:243], v[26:29]
	v_mfma_f32_16x16x32_bf16 v[2:5], v[216:219], v[240:243], v[2:5]
	v_mfma_f32_16x16x32_bf16 v[12:15], v[204:207], v[248:251], v[10:13]
	v_mfma_f32_16x16x32_bf16 v[8:11], v[216:219], v[248:251], v[6:9]
	s_barrier
	s_add_i32 s52, s52, 2
	s_add_u32 s8, s8, 0x100
	s_addc_u32 s9, s9, 0
	s_add_u32 s50, s50, 0x100
	s_addc_u32 s51, s51, 0
	s_cmp_gt_u32 s52, 29
	s_cbranch_scc0 .LBB0_878
	s_and_b64 vcc, exec, s[74:75]
	s_cbranch_vccz .LBB0_881
	s_barrier
